# row passes: per-row counted vmcnt waits (vmcnt retires in issue order) on top of the LDS-free wave sums
# speedup vs baseline: 1.0018x; 1.0018x over previous
.LBB0_562:
	s_lshl_b32 s6, s24, 3
	s_ashr_i32 s7, s6, 31
	v_lshlrev_b32_e32 v49, 2, v116
	s_lshl_b64 s[10:11], s[6:7], 10
	v_mov_b32_e32 v217, s11
	v_or_b32_e32 v216, s10, v49
	v_lshlrev_b64 v[66:67], 1, v[216:217]
	v_lshl_add_u64 v[218:219], s[8:9], 0, v[66:67]
	v_lshl_add_u64 v[66:67], s[38:39], 0, v[66:67]
	global_load_dwordx2 v[90:91], v[218:219], off
	global_load_dwordx2 v[224:225], v[218:219], off offset:512
	global_load_dwordx2 v[222:223], v[218:219], off offset:1024
	global_load_dwordx2 v[220:221], v[218:219], off offset:1536
	global_load_dwordx2 v[86:87], v[66:67], off
	global_load_dwordx2 v[88:89], v[66:67], off offset:512
	global_load_dwordx2 v[92:93], v[66:67], off offset:1024
	global_load_dwordx2 v[230:231], v[66:67], off offset:1536
	s_or_b32 s10, s6, 1
	s_ashr_i32 s11, s10, 31
	s_lshl_b64 s[10:11], s[10:11], 10
	v_or_b32_e32 v196, s10, v49
	s_or_b32 s10, s6, 2
	v_mov_b32_e32 v197, s11
	s_ashr_i32 s11, s10, 31
	s_lshl_b64 s[10:11], s[10:11], 10
	v_or_b32_e32 v176, s10, v49
	s_or_b32 s10, s6, 3
	v_mov_b32_e32 v177, s11
	s_ashr_i32 s11, s10, 31
	s_lshl_b64 s[10:11], s[10:11], 10
	v_lshlrev_b64 v[66:67], 1, v[196:197]
	v_or_b32_e32 v156, s10, v49
	s_or_b32 s10, s6, 4
	v_lshl_add_u64 v[198:199], s[8:9], 0, v[66:67]
	v_lshl_add_u64 v[66:67], s[38:39], 0, v[66:67]
	v_mov_b32_e32 v157, s11
	s_ashr_i32 s11, s10, 31
	global_load_dwordx2 v[206:207], v[198:199], off
	global_load_dwordx2 v[204:205], v[198:199], off offset:512
	global_load_dwordx2 v[202:203], v[198:199], off offset:1024
	global_load_dwordx2 v[200:201], v[198:199], off offset:1536
	global_load_dwordx2 v[214:215], v[66:67], off
	global_load_dwordx2 v[212:213], v[66:67], off offset:512
	global_load_dwordx2 v[210:211], v[66:67], off offset:1024
	global_load_dwordx2 v[208:209], v[66:67], off offset:1536
	v_lshlrev_b64 v[66:67], 1, v[176:177]
	s_lshl_b64 s[10:11], s[10:11], 10
	v_lshl_add_u64 v[178:179], s[8:9], 0, v[66:67]
	v_lshl_add_u64 v[66:67], s[38:39], 0, v[66:67]
	v_or_b32_e32 v134, s10, v49
	s_or_b32 s10, s6, 5
	global_load_dwordx2 v[186:187], v[178:179], off
	global_load_dwordx2 v[184:185], v[178:179], off offset:512
	global_load_dwordx2 v[182:183], v[178:179], off offset:1024
	global_load_dwordx2 v[180:181], v[178:179], off offset:1536
	global_load_dwordx2 v[194:195], v[66:67], off
	global_load_dwordx2 v[192:193], v[66:67], off offset:512
	global_load_dwordx2 v[190:191], v[66:67], off offset:1024
	global_load_dwordx2 v[188:189], v[66:67], off offset:1536
	v_lshlrev_b64 v[66:67], 1, v[156:157]
	v_mov_b32_e32 v135, s11
	s_ashr_i32 s11, s10, 31
	v_lshl_add_u64 v[158:159], s[8:9], 0, v[66:67]
	v_lshl_add_u64 v[66:67], s[38:39], 0, v[66:67]
	s_lshl_b64 s[10:11], s[10:11], 10
	global_load_dwordx2 v[166:167], v[158:159], off
	global_load_dwordx2 v[164:165], v[158:159], off offset:512
	global_load_dwordx2 v[162:163], v[158:159], off offset:1024
	global_load_dwordx2 v[160:161], v[158:159], off offset:1536
	global_load_dwordx2 v[174:175], v[66:67], off
	global_load_dwordx2 v[172:173], v[66:67], off offset:512
	global_load_dwordx2 v[170:171], v[66:67], off offset:1024
	global_load_dwordx2 v[168:169], v[66:67], off offset:1536
	v_lshlrev_b64 v[66:67], 1, v[134:135]
	v_or_b32_e32 v114, s10, v49
	s_or_b32 s10, s6, 6
	v_lshl_add_u64 v[136:137], s[8:9], 0, v[66:67]
	v_lshl_add_u64 v[66:67], s[38:39], 0, v[66:67]
	v_mov_b32_e32 v115, s11
	s_ashr_i32 s11, s10, 31
	global_load_dwordx2 v[146:147], v[136:137], off
	global_load_dwordx2 v[142:143], v[136:137], off offset:512
	global_load_dwordx2 v[140:141], v[136:137], off offset:1024
	global_load_dwordx2 v[138:139], v[136:137], off offset:1536
	global_load_dwordx2 v[154:155], v[66:67], off
	global_load_dwordx2 v[152:153], v[66:67], off offset:512
	global_load_dwordx2 v[150:151], v[66:67], off offset:1024
	global_load_dwordx2 v[148:149], v[66:67], off offset:1536
	v_lshlrev_b64 v[66:67], 1, v[114:115]
	s_lshl_b64 s[10:11], s[10:11], 10
	v_lshl_add_u64 v[116:117], s[8:9], 0, v[66:67]
	v_lshl_add_u64 v[66:67], s[38:39], 0, v[66:67]
	v_mov_b32_e32 v95, s11
	v_or_b32_e32 v94, s10, v49
	s_or_b32 s6, s6, 7
	global_load_dwordx2 v[124:125], v[116:117], off
	global_load_dwordx2 v[122:123], v[116:117], off offset:512
	global_load_dwordx2 v[120:121], v[116:117], off offset:1024
	global_load_dwordx2 v[118:119], v[116:117], off offset:1536
	global_load_dwordx2 v[132:133], v[66:67], off
	global_load_dwordx2 v[130:131], v[66:67], off offset:512
	global_load_dwordx2 v[128:129], v[66:67], off offset:1024
	global_load_dwordx2 v[126:127], v[66:67], off offset:1536
	v_lshlrev_b64 v[66:67], 1, v[94:95]
	s_ashr_i32 s7, s6, 31
	v_lshl_add_u64 v[96:97], s[8:9], 0, v[66:67]
	v_lshl_add_u64 v[66:67], s[38:39], 0, v[66:67]
	s_lshl_b64 s[6:7], s[6:7], 10
	global_load_dwordx2 v[104:105], v[96:97], off
	global_load_dwordx2 v[102:103], v[96:97], off offset:512
	global_load_dwordx2 v[100:101], v[96:97], off offset:1024
	global_load_dwordx2 v[98:99], v[96:97], off offset:1536
	global_load_dwordx2 v[112:113], v[66:67], off
	global_load_dwordx2 v[110:111], v[66:67], off offset:512
	global_load_dwordx2 v[108:109], v[66:67], off offset:1024
	global_load_dwordx2 v[106:107], v[66:67], off offset:1536
	v_mov_b32_e32 v67, s7
	v_or_b32_e32 v66, s6, v49
	v_lshlrev_b64 v[70:71], 1, v[66:67]
	v_lshl_add_u64 v[68:69], s[8:9], 0, v[70:71]
	v_lshl_add_u64 v[78:79], s[38:39], 0, v[70:71]
	global_load_dwordx2 v[76:77], v[68:69], off
	global_load_dwordx2 v[74:75], v[68:69], off offset:512
	global_load_dwordx2 v[72:73], v[68:69], off offset:1024
	global_load_dwordx2 v[70:71], v[68:69], off offset:1536
	global_load_dwordx2 v[84:85], v[78:79], off
	global_load_dwordx2 v[82:83], v[78:79], off offset:512
	global_load_dwordx2 v[80:81], v[78:79], off offset:1024
	s_nop 0
	global_load_dwordx2 v[78:79], v[78:79], off offset:1536
	v_xor_b32_e32 v144, 4, v49
	v_xor_b32_e32 v251, 32, v49
	v_xor_b32_e32 v252, 64, v49
	s_waitcnt vmcnt(56)
	v_pk_add_f32 v[20:21], v[20:21], 1.0 op_sel_hi:[1,0]
	v_pk_add_f32 v[22:23], v[22:23], 1.0 op_sel_hi:[1,0]
	v_pk_mul_f32 v[20:21], v[48:49], v[20:21] op_sel_hi:[0,1]
	v_pk_mul_f32 v[22:23], v[48:49], v[22:23] op_sel_hi:[0,1]
	s_cmp_lg_u64 s[0:1], 0
	s_cselect_b64 s[8:9], -1, 0
	s_cmp_eq_u64 s[0:1], 0
	v_and_b32_e32 v237, 0xffff0000, v86
	v_and_b32_e32 v249, 0xffff0000, v87
	v_lshlrev_b32_e32 v236, 16, v86
	v_lshlrev_b32_e32 v248, 16, v87
	v_mul_f32_e32 v86, v249, v249
	v_and_b32_e32 v243, 0xffff0000, v89
	v_and_b32_e32 v242, 0xffff0000, v88
	v_lshlrev_b32_e32 v232, 16, v92
	v_and_b32_e32 v233, 0xffff0000, v92
	v_mul_f32_e32 v92, v237, v237
	v_pk_fma_f32 v[86:87], v[248:249], v[248:249], v[86:87] op_sel_hi:[1,1,0]
	v_lshlrev_b32_e32 v241, 16, v89
	v_lshlrev_b32_e32 v240, 16, v88
	v_pk_mul_f32 v[88:89], v[242:243], v[242:243]
	v_lshlrev_b32_e32 v234, 16, v93
	v_and_b32_e32 v235, 0xffff0000, v93
	v_lshlrev_b32_e32 v229, 16, v230
	v_pk_fma_f32 v[92:93], v[236:237], v[236:237], v[92:93] op_sel_hi:[1,1,0]
	v_pk_fma_f32 v[88:89], v[240:241], v[240:241], v[88:89]
	v_and_b32_e32 v227, 0xffff0000, v230
	v_mov_b32_e32 v228, v92
	v_mov_b32_e32 v238, v86
	v_mov_b32_e32 v239, v229
	v_mul_f32_e32 v226, v227, v227
	v_pk_add_f32 v[86:87], v[92:93], v[86:87]
	v_pk_mul_f32 v[92:93], v[228:229], v[238:239]
	v_pk_add_f32 v[88:89], v[88:89], v[88:89] op_sel:[0,1] op_sel_hi:[1,0]
	v_mov_b32_e32 v87, v93
	v_mov_b32_e32 v89, v226
	v_lshlrev_b32_e32 v230, 16, v231
	v_and_b32_e32 v231, 0xffff0000, v231
	v_pk_add_f32 v[86:87], v[86:87], v[88:89]
	v_mul_f32_e32 v88, v233, v233
	v_mul_f32_e32 v92, v235, v235
	v_mul_f32_e32 v246, v230, v230
	v_mul_f32_e32 v250, v231, v231
	v_pk_fma_f32 v[88:89], v[232:233], v[232:233], v[88:89] op_sel_hi:[1,1,0]
	v_pk_fma_f32 v[92:93], v[234:235], v[234:235], v[92:93] op_sel_hi:[1,1,0]
	v_mov_b32_e32 v89, v246
	v_mov_b32_e32 v93, v250
	v_pk_add_f32 v[88:89], v[88:89], v[92:93]
	v_xor_b32_e32 v228, 8, v49
	v_pk_add_f32 v[86:87], v[86:87], v[88:89]
	v_xor_b32_e32 v250, 16, v49
	v_add_f32_e32 v86, v86, v87
	s_nop 1
	v_mov_b32_dpp v87, v86 quad_perm:[1,0,3,2] row_mask:0xf bank_mask:0xf
	v_xor_b32_e32 v246, 0x80, v49
	v_pk_mul_f32 v[88:89], v[18:19], v[22:23]
	v_and_b32_e32 v19, 0xffff0000, v91
	s_waitcnt lgkmcnt(0)
	v_add_f32_e32 v86, v86, v87
	s_nop 1
	v_mov_b32_dpp v87, v86 quad_perm:[2,3,0,1] row_mask:0xf bank_mask:0xf
	s_waitcnt lgkmcnt(0)
	v_add_f32_e32 v86, v86, v87
	s_nop 1
	v_mov_b32_dpp v87, v86 row_half_mirror row_mask:0xf bank_mask:0xf
	s_waitcnt lgkmcnt(0)
	v_add_f32_e32 v86, v86, v87
	s_nop 1
	v_mov_b32_dpp v87, v86 row_mirror row_mask:0xf bank_mask:0xf
	s_waitcnt lgkmcnt(0)
	v_add_f32_e32 v92, v86, v87
	v_pk_mul_f32 v[86:87], v[16:17], v[20:21]
	v_lshlrev_b32_e32 v16, 16, v90
	s_waitcnt lgkmcnt(0)
	s_nop 0
	v_readlane_b32 s98, v92, 32
	v_readlane_b32 s100, v92, 48
	s_nop 1
	v_mov_b32_e32 v93, s100
	v_add_f32_e32 v93, s98, v93
	v_readlane_b32 s98, v92, 0
	v_readlane_b32 s100, v92, 16
	s_nop 1
	v_mov_b32_e32 v17, s100
	v_add_f32_e32 v17, s98, v17
	v_add_f32_e32 v17, v17, v93
	s_waitcnt lgkmcnt(0)
	v_fmamk_f32 v17, v17, 0x3a800000, v247
	v_mul_f32_e32 v18, 0x4b800000, v17
	v_cmp_gt_f32_e32 vcc, s35, v17
	s_nop 1
	v_cndmask_b32_e32 v17, v17, v18, vcc
	v_rsq_f32_e32 v20, v17
	v_and_b32_e32 v17, 0xffff0000, v90
	v_lshlrev_b32_e32 v18, 16, v91
	v_mul_f32_e32 v21, 0x45800000, v20
	v_cndmask_b32_e32 v238, v20, v21, vcc
	v_pk_mul_f32 v[20:21], v[238:239], v[236:237] op_sel_hi:[0,1]
	v_pk_mul_f32 v[22:23], v[238:239], v[248:249] op_sel_hi:[0,1]
	v_pk_fma_f32 v[18:19], v[88:89], v[22:23], v[18:19]
	v_pk_fma_f32 v[16:17], v[86:87], v[20:21], v[16:17]
	v_lshl_add_u64 v[236:237], v[216:217], 2, s[0:1]
	s_cbranch_scc1 .LBB0_573
	s_waitcnt vmcnt(0)
	global_store_dwordx4 v[236:237], v[16:19], off
	s_cbranch_execnz .LBB0_565

.LBB0_581:
	s_waitcnt vmcnt(56)
	v_and_b32_e32 v17, 0xffff0000, v214
	v_and_b32_e32 v19, 0xffff0000, v215
	v_lshlrev_b32_e32 v16, 16, v214
	v_lshlrev_b32_e32 v18, 16, v215
	v_mul_f32_e32 v20, v19, v19
	v_and_b32_e32 v23, 0xffff0000, v213
	v_and_b32_e32 v22, 0xffff0000, v212
	v_and_b32_e32 v29, 0xffff0000, v208
	v_mul_f32_e32 v28, v17, v17
	v_pk_fma_f32 v[42:43], v[18:19], v[18:19], v[20:21] op_sel_hi:[1,1,0]
	v_lshlrev_b32_e32 v21, 16, v213
	v_lshlrev_b32_e32 v20, 16, v212
	v_pk_mul_f32 v[24:25], v[22:23], v[22:23]
	v_lshlrev_b32_e32 v31, 16, v208
	v_pk_fma_f32 v[46:47], v[16:17], v[16:17], v[28:29] op_sel_hi:[1,1,0]
	v_pk_fma_f32 v[44:45], v[20:21], v[20:21], v[24:25]
	v_mov_b32_e32 v30, v46
	v_mov_b32_e32 v48, v42
	v_mov_b32_e32 v49, v31
	v_and_b32_e32 v25, 0xffff0000, v210
	v_mul_f32_e32 v208, v29, v29
	v_pk_add_f32 v[42:43], v[46:47], v[42:43]
	v_pk_mul_f32 v[46:47], v[30:31], v[48:49]
	v_pk_add_f32 v[44:45], v[44:45], v[44:45] op_sel:[0,1] op_sel_hi:[1,0]
	v_lshlrev_b32_e32 v24, 16, v210
	v_and_b32_e32 v27, 0xffff0000, v211
	v_mov_b32_e32 v43, v47
	v_mov_b32_e32 v45, v208
	v_mul_f32_e32 v28, v25, v25
	v_lshlrev_b32_e32 v26, 16, v211
	v_lshlrev_b32_e32 v40, 16, v209
	v_and_b32_e32 v41, 0xffff0000, v209
	v_pk_add_f32 v[42:43], v[42:43], v[44:45]
	v_pk_fma_f32 v[44:45], v[24:25], v[24:25], v[28:29] op_sel_hi:[1,1,0]
	v_mul_f32_e32 v28, v27, v27
	v_mul_f32_e32 v209, v40, v40
	v_mul_f32_e32 v210, v41, v41
	v_pk_fma_f32 v[46:47], v[26:27], v[26:27], v[28:29] op_sel_hi:[1,1,0]
	v_mov_b32_e32 v45, v209
	v_mov_b32_e32 v47, v210
	v_pk_add_f32 v[44:45], v[44:45], v[46:47]
	v_lshlrev_b32_e32 v46, 16, v207
	v_pk_add_f32 v[42:43], v[42:43], v[44:45]
	v_lshlrev_b32_e32 v44, 16, v206
	v_add_f32_e32 v28, v42, v43
	s_nop 1
	v_mov_b32_dpp v30, v28 quad_perm:[1,0,3,2] row_mask:0xf bank_mask:0xf
	v_and_b32_e32 v45, 0xffff0000, v206
	v_and_b32_e32 v47, 0xffff0000, v207
	s_waitcnt lgkmcnt(0)
	v_add_f32_e32 v28, v28, v30
	s_nop 1
	v_mov_b32_dpp v30, v28 quad_perm:[2,3,0,1] row_mask:0xf bank_mask:0xf
	s_waitcnt lgkmcnt(0)
	v_add_f32_e32 v28, v28, v30
	s_nop 1
	v_mov_b32_dpp v30, v28 row_half_mirror row_mask:0xf bank_mask:0xf
	s_waitcnt lgkmcnt(0)
	v_add_f32_e32 v28, v28, v30
	s_nop 1
	v_mov_b32_dpp v30, v28 row_mirror row_mask:0xf bank_mask:0xf
	s_waitcnt lgkmcnt(0)
	v_add_f32_e32 v28, v28, v30
	s_waitcnt lgkmcnt(0)
	s_nop 0
	v_readlane_b32 s98, v28, 32
	v_readlane_b32 s100, v28, 48
	s_nop 1
	v_mov_b32_e32 v30, s100
	v_add_f32_e32 v30, s98, v30
	v_readlane_b32 s98, v28, 0
	v_readlane_b32 s100, v28, 16
	s_nop 1
	v_mov_b32_e32 v28, s100
	v_add_f32_e32 v28, s98, v28
	v_add_f32_e32 v28, v28, v30
	s_waitcnt lgkmcnt(0)
	v_fmamk_f32 v28, v28, 0x3a800000, v247
	v_mul_f32_e32 v30, 0x4b800000, v28
	v_cmp_gt_f32_e32 vcc, s35, v28
	s_nop 1
	v_cndmask_b32_e32 v28, v28, v30, vcc
	v_rsq_f32_e32 v28, v28
	s_nop 0
	v_mul_f32_e32 v30, 0x45800000, v28
	v_cndmask_b32_e32 v42, v28, v30, vcc
	v_pk_mul_f32 v[16:17], v[42:43], v[16:17] op_sel_hi:[0,1]
	v_pk_mul_f32 v[18:19], v[42:43], v[18:19] op_sel_hi:[0,1]
	v_pk_fma_f32 v[18:19], v[88:89], v[18:19], v[46:47]
	v_pk_fma_f32 v[16:17], v[86:87], v[16:17], v[44:45]
	s_and_b64 vcc, exec, s[6:7]
	v_lshl_add_u64 v[44:45], v[196:197], 2, s[0:1]
	s_cbranch_vccnz .LBB0_835
	global_store_dwordx4 v[44:45], v[16:19], off
	s_cbranch_execnz .LBB0_584

.LBB0_595:
	s_waitcnt vmcnt(56)
	v_and_b32_e32 v17, 0xffff0000, v194
	v_and_b32_e32 v19, 0xffff0000, v195
	v_lshlrev_b32_e32 v16, 16, v194
	v_lshlrev_b32_e32 v18, 16, v195
	v_mul_f32_e32 v20, v19, v19
	v_and_b32_e32 v23, 0xffff0000, v193
	v_and_b32_e32 v22, 0xffff0000, v192
	v_and_b32_e32 v29, 0xffff0000, v188
	v_mul_f32_e32 v28, v17, v17
	v_pk_fma_f32 v[42:43], v[18:19], v[18:19], v[20:21] op_sel_hi:[1,1,0]
	v_lshlrev_b32_e32 v21, 16, v193
	v_lshlrev_b32_e32 v20, 16, v192
	v_pk_mul_f32 v[24:25], v[22:23], v[22:23]
	v_lshlrev_b32_e32 v31, 16, v188
	v_pk_fma_f32 v[46:47], v[16:17], v[16:17], v[28:29] op_sel_hi:[1,1,0]
	v_pk_fma_f32 v[44:45], v[20:21], v[20:21], v[24:25]
	v_mov_b32_e32 v30, v46
	v_mov_b32_e32 v48, v42
	v_mov_b32_e32 v49, v31
	v_and_b32_e32 v25, 0xffff0000, v190
	v_mul_f32_e32 v188, v29, v29
	v_pk_add_f32 v[42:43], v[46:47], v[42:43]
	v_pk_mul_f32 v[46:47], v[30:31], v[48:49]
	v_pk_add_f32 v[44:45], v[44:45], v[44:45] op_sel:[0,1] op_sel_hi:[1,0]
	v_lshlrev_b32_e32 v24, 16, v190
	v_and_b32_e32 v27, 0xffff0000, v191
	v_mov_b32_e32 v43, v47
	v_mov_b32_e32 v45, v188
	v_mul_f32_e32 v28, v25, v25
	v_lshlrev_b32_e32 v26, 16, v191
	v_lshlrev_b32_e32 v40, 16, v189
	v_and_b32_e32 v41, 0xffff0000, v189
	v_pk_add_f32 v[42:43], v[42:43], v[44:45]
	v_pk_fma_f32 v[44:45], v[24:25], v[24:25], v[28:29] op_sel_hi:[1,1,0]
	v_mul_f32_e32 v28, v27, v27
	v_mul_f32_e32 v189, v40, v40
	v_mul_f32_e32 v190, v41, v41
	v_pk_fma_f32 v[46:47], v[26:27], v[26:27], v[28:29] op_sel_hi:[1,1,0]
	v_mov_b32_e32 v45, v189
	v_mov_b32_e32 v47, v190
	v_pk_add_f32 v[44:45], v[44:45], v[46:47]
	v_lshlrev_b32_e32 v46, 16, v187
	v_pk_add_f32 v[42:43], v[42:43], v[44:45]
	v_lshlrev_b32_e32 v44, 16, v186
	v_add_f32_e32 v28, v42, v43
	s_nop 1
	v_mov_b32_dpp v30, v28 quad_perm:[1,0,3,2] row_mask:0xf bank_mask:0xf
	v_and_b32_e32 v45, 0xffff0000, v186
	v_and_b32_e32 v47, 0xffff0000, v187
	s_waitcnt lgkmcnt(0)
	v_add_f32_e32 v28, v28, v30
	s_nop 1
	v_mov_b32_dpp v30, v28 quad_perm:[2,3,0,1] row_mask:0xf bank_mask:0xf
	s_waitcnt lgkmcnt(0)
	v_add_f32_e32 v28, v28, v30
	s_nop 1
	v_mov_b32_dpp v30, v28 row_half_mirror row_mask:0xf bank_mask:0xf
	s_waitcnt lgkmcnt(0)
	v_add_f32_e32 v28, v28, v30
	s_nop 1
	v_mov_b32_dpp v30, v28 row_mirror row_mask:0xf bank_mask:0xf
	s_waitcnt lgkmcnt(0)
	v_add_f32_e32 v28, v28, v30
	s_waitcnt lgkmcnt(0)
	s_nop 0
	v_readlane_b32 s98, v28, 32
	v_readlane_b32 s100, v28, 48
	s_nop 1
	v_mov_b32_e32 v30, s100
	v_add_f32_e32 v30, s98, v30
	v_readlane_b32 s98, v28, 0
	v_readlane_b32 s100, v28, 16
	s_nop 1
	v_mov_b32_e32 v28, s100
	v_add_f32_e32 v28, s98, v28
	v_add_f32_e32 v28, v28, v30
	s_waitcnt lgkmcnt(0)
	v_fmamk_f32 v28, v28, 0x3a800000, v247
	v_mul_f32_e32 v30, 0x4b800000, v28
	v_cmp_gt_f32_e32 vcc, s35, v28
	s_nop 1
	v_cndmask_b32_e32 v28, v28, v30, vcc
	v_rsq_f32_e32 v28, v28
	s_nop 0
	v_mul_f32_e32 v30, 0x45800000, v28
	v_cndmask_b32_e32 v42, v28, v30, vcc
	v_pk_mul_f32 v[16:17], v[42:43], v[16:17] op_sel_hi:[0,1]
	v_pk_mul_f32 v[18:19], v[42:43], v[18:19] op_sel_hi:[0,1]
	v_pk_fma_f32 v[18:19], v[88:89], v[18:19], v[46:47]
	v_pk_fma_f32 v[16:17], v[86:87], v[16:17], v[44:45]
	s_and_b64 vcc, exec, s[6:7]
	v_lshl_add_u64 v[44:45], v[176:177], 2, s[0:1]
	s_cbranch_vccnz .LBB0_839
	global_store_dwordx4 v[44:45], v[16:19], off
	s_cbranch_execnz .LBB0_598

.LBB0_609:
	s_waitcnt vmcnt(56)
	v_and_b32_e32 v17, 0xffff0000, v174
	v_and_b32_e32 v19, 0xffff0000, v175
	v_lshlrev_b32_e32 v16, 16, v174
	v_lshlrev_b32_e32 v18, 16, v175
	v_mul_f32_e32 v20, v19, v19
	v_and_b32_e32 v23, 0xffff0000, v173
	v_and_b32_e32 v22, 0xffff0000, v172
	v_and_b32_e32 v29, 0xffff0000, v168
	v_mul_f32_e32 v28, v17, v17
	v_pk_fma_f32 v[42:43], v[18:19], v[18:19], v[20:21] op_sel_hi:[1,1,0]
	v_lshlrev_b32_e32 v21, 16, v173
	v_lshlrev_b32_e32 v20, 16, v172
	v_pk_mul_f32 v[24:25], v[22:23], v[22:23]
	v_lshlrev_b32_e32 v31, 16, v168
	v_pk_fma_f32 v[46:47], v[16:17], v[16:17], v[28:29] op_sel_hi:[1,1,0]
	v_pk_fma_f32 v[44:45], v[20:21], v[20:21], v[24:25]
	v_mov_b32_e32 v30, v46
	v_mov_b32_e32 v48, v42
	v_mov_b32_e32 v49, v31
	v_and_b32_e32 v25, 0xffff0000, v170
	v_mul_f32_e32 v168, v29, v29
	v_pk_add_f32 v[42:43], v[46:47], v[42:43]
	v_pk_mul_f32 v[46:47], v[30:31], v[48:49]
	v_pk_add_f32 v[44:45], v[44:45], v[44:45] op_sel:[0,1] op_sel_hi:[1,0]
	v_lshlrev_b32_e32 v24, 16, v170
	v_and_b32_e32 v27, 0xffff0000, v171
	v_mov_b32_e32 v43, v47
	v_mov_b32_e32 v45, v168
	v_mul_f32_e32 v28, v25, v25
	v_lshlrev_b32_e32 v26, 16, v171
	v_lshlrev_b32_e32 v40, 16, v169
	v_and_b32_e32 v41, 0xffff0000, v169
	v_pk_add_f32 v[42:43], v[42:43], v[44:45]
	v_pk_fma_f32 v[44:45], v[24:25], v[24:25], v[28:29] op_sel_hi:[1,1,0]
	v_mul_f32_e32 v28, v27, v27
	v_mul_f32_e32 v169, v40, v40
	v_mul_f32_e32 v170, v41, v41
	v_pk_fma_f32 v[46:47], v[26:27], v[26:27], v[28:29] op_sel_hi:[1,1,0]
	v_mov_b32_e32 v45, v169
	v_mov_b32_e32 v47, v170
	v_pk_add_f32 v[44:45], v[44:45], v[46:47]
	v_lshlrev_b32_e32 v46, 16, v167
	v_pk_add_f32 v[42:43], v[42:43], v[44:45]
	v_lshlrev_b32_e32 v44, 16, v166
	v_add_f32_e32 v28, v42, v43
	s_nop 1
	v_mov_b32_dpp v30, v28 quad_perm:[1,0,3,2] row_mask:0xf bank_mask:0xf
	v_and_b32_e32 v45, 0xffff0000, v166
	v_and_b32_e32 v47, 0xffff0000, v167
	s_waitcnt lgkmcnt(0)
	v_add_f32_e32 v28, v28, v30
	s_nop 1
	v_mov_b32_dpp v30, v28 quad_perm:[2,3,0,1] row_mask:0xf bank_mask:0xf
	s_waitcnt lgkmcnt(0)
	v_add_f32_e32 v28, v28, v30
	s_nop 1
	v_mov_b32_dpp v30, v28 row_half_mirror row_mask:0xf bank_mask:0xf
	s_waitcnt lgkmcnt(0)
	v_add_f32_e32 v28, v28, v30
	s_nop 1
	v_mov_b32_dpp v30, v28 row_mirror row_mask:0xf bank_mask:0xf
	s_waitcnt lgkmcnt(0)
	v_add_f32_e32 v28, v28, v30
	s_waitcnt lgkmcnt(0)
	s_nop 0
	v_readlane_b32 s98, v28, 32
	v_readlane_b32 s100, v28, 48
	s_nop 1
	v_mov_b32_e32 v30, s100
	v_add_f32_e32 v30, s98, v30
	v_readlane_b32 s98, v28, 0
	v_readlane_b32 s100, v28, 16
	s_nop 1
	v_mov_b32_e32 v28, s100
	v_add_f32_e32 v28, s98, v28
	v_add_f32_e32 v28, v28, v30
	s_waitcnt lgkmcnt(0)
	v_fmamk_f32 v28, v28, 0x3a800000, v247
	v_mul_f32_e32 v30, 0x4b800000, v28
	v_cmp_gt_f32_e32 vcc, s35, v28
	s_nop 1
	v_cndmask_b32_e32 v28, v28, v30, vcc
	v_rsq_f32_e32 v28, v28
	s_nop 0
	v_mul_f32_e32 v30, 0x45800000, v28
	v_cndmask_b32_e32 v42, v28, v30, vcc
	v_pk_mul_f32 v[16:17], v[42:43], v[16:17] op_sel_hi:[0,1]
	v_pk_mul_f32 v[18:19], v[42:43], v[18:19] op_sel_hi:[0,1]
	v_pk_fma_f32 v[18:19], v[88:89], v[18:19], v[46:47]
	v_pk_fma_f32 v[16:17], v[86:87], v[16:17], v[44:45]
	s_and_b64 vcc, exec, s[6:7]
	v_lshl_add_u64 v[44:45], v[156:157], 2, s[0:1]
	s_cbranch_vccnz .LBB0_843
	global_store_dwordx4 v[44:45], v[16:19], off
	s_cbranch_execnz .LBB0_612

.LBB0_623:
	s_waitcnt vmcnt(56)
	v_and_b32_e32 v17, 0xffff0000, v154
	v_and_b32_e32 v19, 0xffff0000, v155
	v_lshlrev_b32_e32 v16, 16, v154
	v_lshlrev_b32_e32 v18, 16, v155
	v_mul_f32_e32 v20, v19, v19
	v_and_b32_e32 v23, 0xffff0000, v153
	v_and_b32_e32 v22, 0xffff0000, v152
	v_and_b32_e32 v29, 0xffff0000, v148
	v_mul_f32_e32 v28, v17, v17
	v_pk_fma_f32 v[42:43], v[18:19], v[18:19], v[20:21] op_sel_hi:[1,1,0]
	v_lshlrev_b32_e32 v21, 16, v153
	v_lshlrev_b32_e32 v20, 16, v152
	v_pk_mul_f32 v[24:25], v[22:23], v[22:23]
	v_lshlrev_b32_e32 v31, 16, v148
	v_pk_fma_f32 v[46:47], v[16:17], v[16:17], v[28:29] op_sel_hi:[1,1,0]
	v_pk_fma_f32 v[44:45], v[20:21], v[20:21], v[24:25]
	v_mov_b32_e32 v30, v46
	v_mov_b32_e32 v48, v42
	v_mov_b32_e32 v49, v31
	v_and_b32_e32 v25, 0xffff0000, v150
	v_mul_f32_e32 v148, v29, v29
	v_pk_add_f32 v[42:43], v[46:47], v[42:43]
	v_pk_mul_f32 v[46:47], v[30:31], v[48:49]
	v_pk_add_f32 v[44:45], v[44:45], v[44:45] op_sel:[0,1] op_sel_hi:[1,0]
	v_lshlrev_b32_e32 v24, 16, v150
	v_and_b32_e32 v27, 0xffff0000, v151
	v_mov_b32_e32 v43, v47
	v_mov_b32_e32 v45, v148
	v_mul_f32_e32 v28, v25, v25
	v_lshlrev_b32_e32 v26, 16, v151
	v_lshlrev_b32_e32 v40, 16, v149
	v_and_b32_e32 v41, 0xffff0000, v149
	v_pk_add_f32 v[42:43], v[42:43], v[44:45]
	v_pk_fma_f32 v[44:45], v[24:25], v[24:25], v[28:29] op_sel_hi:[1,1,0]
	v_mul_f32_e32 v28, v27, v27
	v_mul_f32_e32 v149, v40, v40
	v_mul_f32_e32 v150, v41, v41
	v_pk_fma_f32 v[46:47], v[26:27], v[26:27], v[28:29] op_sel_hi:[1,1,0]
	v_mov_b32_e32 v45, v149
	v_mov_b32_e32 v47, v150
	v_pk_add_f32 v[44:45], v[44:45], v[46:47]
	v_lshlrev_b32_e32 v46, 16, v147
	v_pk_add_f32 v[42:43], v[42:43], v[44:45]
	v_lshlrev_b32_e32 v44, 16, v146
	v_add_f32_e32 v28, v42, v43
	s_nop 1
	v_mov_b32_dpp v30, v28 quad_perm:[1,0,3,2] row_mask:0xf bank_mask:0xf
	v_and_b32_e32 v45, 0xffff0000, v146
	v_and_b32_e32 v47, 0xffff0000, v147
	s_waitcnt lgkmcnt(0)
	v_add_f32_e32 v28, v28, v30
	s_nop 1
	v_mov_b32_dpp v30, v28 quad_perm:[2,3,0,1] row_mask:0xf bank_mask:0xf
	s_waitcnt lgkmcnt(0)
	v_add_f32_e32 v28, v28, v30
	s_nop 1
	v_mov_b32_dpp v30, v28 row_half_mirror row_mask:0xf bank_mask:0xf
	s_waitcnt lgkmcnt(0)
	v_add_f32_e32 v28, v28, v30
	s_nop 1
	v_mov_b32_dpp v30, v28 row_mirror row_mask:0xf bank_mask:0xf
	s_waitcnt lgkmcnt(0)
	v_add_f32_e32 v28, v28, v30
	s_waitcnt lgkmcnt(0)
	s_nop 0
	v_readlane_b32 s98, v28, 32
	v_readlane_b32 s100, v28, 48
	s_nop 1
	v_mov_b32_e32 v30, s100
	v_add_f32_e32 v30, s98, v30
	v_readlane_b32 s98, v28, 0
	v_readlane_b32 s100, v28, 16
	s_nop 1
	v_mov_b32_e32 v28, s100
	v_add_f32_e32 v28, s98, v28
	v_add_f32_e32 v28, v28, v30
	s_waitcnt lgkmcnt(0)
	v_fmamk_f32 v28, v28, 0x3a800000, v247
	v_mul_f32_e32 v30, 0x4b800000, v28
	v_cmp_gt_f32_e32 vcc, s35, v28
	s_nop 1
	v_cndmask_b32_e32 v28, v28, v30, vcc
	v_rsq_f32_e32 v28, v28
	s_nop 0
	v_mul_f32_e32 v30, 0x45800000, v28
	v_cndmask_b32_e32 v42, v28, v30, vcc
	v_pk_mul_f32 v[16:17], v[42:43], v[16:17] op_sel_hi:[0,1]
	v_pk_mul_f32 v[18:19], v[42:43], v[18:19] op_sel_hi:[0,1]
	v_pk_fma_f32 v[18:19], v[88:89], v[18:19], v[46:47]
	v_pk_fma_f32 v[16:17], v[86:87], v[16:17], v[44:45]
	s_and_b64 vcc, exec, s[6:7]
	v_lshl_add_u64 v[44:45], v[134:135], 2, s[0:1]
	s_cbranch_vccnz .LBB0_847
	global_store_dwordx4 v[44:45], v[16:19], off
	s_cbranch_execnz .LBB0_626

.LBB0_637:
	s_waitcnt vmcnt(56)
	v_and_b32_e32 v17, 0xffff0000, v132
	v_and_b32_e32 v19, 0xffff0000, v133
	v_lshlrev_b32_e32 v16, 16, v132
	v_lshlrev_b32_e32 v18, 16, v133
	v_mul_f32_e32 v20, v19, v19
	v_and_b32_e32 v23, 0xffff0000, v131
	v_and_b32_e32 v22, 0xffff0000, v130
	v_and_b32_e32 v29, 0xffff0000, v126
	v_mul_f32_e32 v28, v17, v17
	v_pk_fma_f32 v[42:43], v[18:19], v[18:19], v[20:21] op_sel_hi:[1,1,0]
	v_lshlrev_b32_e32 v21, 16, v131
	v_lshlrev_b32_e32 v20, 16, v130
	v_pk_mul_f32 v[24:25], v[22:23], v[22:23]
	v_lshlrev_b32_e32 v31, 16, v126
	v_pk_fma_f32 v[46:47], v[16:17], v[16:17], v[28:29] op_sel_hi:[1,1,0]
	v_pk_fma_f32 v[44:45], v[20:21], v[20:21], v[24:25]
	v_mov_b32_e32 v30, v46
	v_mov_b32_e32 v48, v42
	v_mov_b32_e32 v49, v31
	v_and_b32_e32 v25, 0xffff0000, v128
	v_mul_f32_e32 v126, v29, v29
	v_pk_add_f32 v[42:43], v[46:47], v[42:43]
	v_pk_mul_f32 v[46:47], v[30:31], v[48:49]
	v_pk_add_f32 v[44:45], v[44:45], v[44:45] op_sel:[0,1] op_sel_hi:[1,0]
	v_lshlrev_b32_e32 v24, 16, v128
	v_and_b32_e32 v27, 0xffff0000, v129
	v_mov_b32_e32 v43, v47
	v_mov_b32_e32 v45, v126
	v_mul_f32_e32 v28, v25, v25
	v_lshlrev_b32_e32 v26, 16, v129
	v_lshlrev_b32_e32 v40, 16, v127
	v_and_b32_e32 v41, 0xffff0000, v127
	v_pk_add_f32 v[42:43], v[42:43], v[44:45]
	v_pk_fma_f32 v[44:45], v[24:25], v[24:25], v[28:29] op_sel_hi:[1,1,0]
	v_mul_f32_e32 v28, v27, v27
	v_mul_f32_e32 v127, v40, v40
	v_mul_f32_e32 v128, v41, v41
	v_pk_fma_f32 v[46:47], v[26:27], v[26:27], v[28:29] op_sel_hi:[1,1,0]
	v_mov_b32_e32 v45, v127
	v_mov_b32_e32 v47, v128
	v_pk_add_f32 v[44:45], v[44:45], v[46:47]
	v_lshlrev_b32_e32 v46, 16, v125
	v_pk_add_f32 v[42:43], v[42:43], v[44:45]
	v_lshlrev_b32_e32 v44, 16, v124
	v_add_f32_e32 v28, v42, v43
	s_nop 1
	v_mov_b32_dpp v30, v28 quad_perm:[1,0,3,2] row_mask:0xf bank_mask:0xf
	v_and_b32_e32 v45, 0xffff0000, v124
	v_and_b32_e32 v47, 0xffff0000, v125
	s_waitcnt lgkmcnt(0)
	v_add_f32_e32 v28, v28, v30
	s_nop 1
	v_mov_b32_dpp v30, v28 quad_perm:[2,3,0,1] row_mask:0xf bank_mask:0xf
	s_waitcnt lgkmcnt(0)
	v_add_f32_e32 v28, v28, v30
	s_nop 1
	v_mov_b32_dpp v30, v28 row_half_mirror row_mask:0xf bank_mask:0xf
	s_waitcnt lgkmcnt(0)
	v_add_f32_e32 v28, v28, v30
	s_nop 1
	v_mov_b32_dpp v30, v28 row_mirror row_mask:0xf bank_mask:0xf
	s_waitcnt lgkmcnt(0)
	v_add_f32_e32 v28, v28, v30
	s_waitcnt lgkmcnt(0)
	s_nop 0
	v_readlane_b32 s98, v28, 32
	v_readlane_b32 s100, v28, 48
	s_nop 1
	v_mov_b32_e32 v30, s100
	v_add_f32_e32 v30, s98, v30
	v_readlane_b32 s98, v28, 0
	v_readlane_b32 s100, v28, 16
	s_nop 1
	v_mov_b32_e32 v28, s100
	v_add_f32_e32 v28, s98, v28
	v_add_f32_e32 v28, v28, v30
	s_waitcnt lgkmcnt(0)
	v_fmamk_f32 v28, v28, 0x3a800000, v247
	v_mul_f32_e32 v30, 0x4b800000, v28
	v_cmp_gt_f32_e32 vcc, s35, v28
	s_nop 1
	v_cndmask_b32_e32 v28, v28, v30, vcc
	v_rsq_f32_e32 v28, v28
	s_nop 0
	v_mul_f32_e32 v30, 0x45800000, v28
	v_cndmask_b32_e32 v42, v28, v30, vcc
	v_pk_mul_f32 v[16:17], v[42:43], v[16:17] op_sel_hi:[0,1]
	v_pk_mul_f32 v[18:19], v[42:43], v[18:19] op_sel_hi:[0,1]
	v_pk_fma_f32 v[18:19], v[88:89], v[18:19], v[46:47]
	v_pk_fma_f32 v[16:17], v[86:87], v[16:17], v[44:45]
	s_and_b64 vcc, exec, s[6:7]
	v_lshl_add_u64 v[44:45], v[114:115], 2, s[0:1]
	s_cbranch_vccnz .LBB0_851
	global_store_dwordx4 v[44:45], v[16:19], off
	s_cbranch_execnz .LBB0_640

.LBB0_651:
	s_waitcnt vmcnt(56)
	v_and_b32_e32 v17, 0xffff0000, v112
	v_and_b32_e32 v19, 0xffff0000, v113
	v_lshlrev_b32_e32 v16, 16, v112
	v_lshlrev_b32_e32 v18, 16, v113
	v_mul_f32_e32 v20, v19, v19
	v_and_b32_e32 v23, 0xffff0000, v111
	v_and_b32_e32 v22, 0xffff0000, v110
	v_and_b32_e32 v29, 0xffff0000, v106
	v_mul_f32_e32 v28, v17, v17
	v_pk_fma_f32 v[42:43], v[18:19], v[18:19], v[20:21] op_sel_hi:[1,1,0]
	v_lshlrev_b32_e32 v21, 16, v111
	v_lshlrev_b32_e32 v20, 16, v110
	v_pk_mul_f32 v[24:25], v[22:23], v[22:23]
	v_lshlrev_b32_e32 v31, 16, v106
	v_pk_fma_f32 v[46:47], v[16:17], v[16:17], v[28:29] op_sel_hi:[1,1,0]
	v_pk_fma_f32 v[44:45], v[20:21], v[20:21], v[24:25]
	v_mov_b32_e32 v30, v46
	v_mov_b32_e32 v48, v42
	v_mov_b32_e32 v49, v31
	v_and_b32_e32 v25, 0xffff0000, v108
	v_mul_f32_e32 v106, v29, v29
	v_pk_add_f32 v[42:43], v[46:47], v[42:43]
	v_pk_mul_f32 v[46:47], v[30:31], v[48:49]
	v_pk_add_f32 v[44:45], v[44:45], v[44:45] op_sel:[0,1] op_sel_hi:[1,0]
	v_lshlrev_b32_e32 v24, 16, v108
	v_and_b32_e32 v27, 0xffff0000, v109
	v_mov_b32_e32 v43, v47
	v_mov_b32_e32 v45, v106
	v_mul_f32_e32 v28, v25, v25
	v_lshlrev_b32_e32 v26, 16, v109
	v_lshlrev_b32_e32 v40, 16, v107
	v_and_b32_e32 v41, 0xffff0000, v107
	v_pk_add_f32 v[42:43], v[42:43], v[44:45]
	v_pk_fma_f32 v[44:45], v[24:25], v[24:25], v[28:29] op_sel_hi:[1,1,0]
	v_mul_f32_e32 v28, v27, v27
	v_mul_f32_e32 v107, v40, v40
	v_mul_f32_e32 v108, v41, v41
	v_pk_fma_f32 v[46:47], v[26:27], v[26:27], v[28:29] op_sel_hi:[1,1,0]
	v_mov_b32_e32 v45, v107
	v_mov_b32_e32 v47, v108
	v_pk_add_f32 v[44:45], v[44:45], v[46:47]
	v_lshlrev_b32_e32 v46, 16, v105
	v_pk_add_f32 v[42:43], v[42:43], v[44:45]
	v_lshlrev_b32_e32 v44, 16, v104
	v_add_f32_e32 v28, v42, v43
	s_nop 1
	v_mov_b32_dpp v30, v28 quad_perm:[1,0,3,2] row_mask:0xf bank_mask:0xf
	v_and_b32_e32 v45, 0xffff0000, v104
	v_and_b32_e32 v47, 0xffff0000, v105
	s_waitcnt lgkmcnt(0)
	v_add_f32_e32 v28, v28, v30
	s_nop 1
	v_mov_b32_dpp v30, v28 quad_perm:[2,3,0,1] row_mask:0xf bank_mask:0xf
	s_waitcnt lgkmcnt(0)
	v_add_f32_e32 v28, v28, v30
	s_nop 1
	v_mov_b32_dpp v30, v28 row_half_mirror row_mask:0xf bank_mask:0xf
	s_waitcnt lgkmcnt(0)
	v_add_f32_e32 v28, v28, v30
	s_nop 1
	v_mov_b32_dpp v30, v28 row_mirror row_mask:0xf bank_mask:0xf
	s_waitcnt lgkmcnt(0)
	v_add_f32_e32 v28, v28, v30
	s_waitcnt lgkmcnt(0)
	s_nop 0
	v_readlane_b32 s98, v28, 32
	v_readlane_b32 s100, v28, 48
	s_nop 1
	v_mov_b32_e32 v30, s100
	v_add_f32_e32 v30, s98, v30
	v_readlane_b32 s98, v28, 0
	v_readlane_b32 s100, v28, 16
	s_nop 1
	v_mov_b32_e32 v28, s100
	v_add_f32_e32 v28, s98, v28
	v_add_f32_e32 v28, v28, v30
	s_waitcnt lgkmcnt(0)
	v_fmamk_f32 v28, v28, 0x3a800000, v247
	v_mul_f32_e32 v30, 0x4b800000, v28
	v_cmp_gt_f32_e32 vcc, s35, v28
	s_nop 1
	v_cndmask_b32_e32 v28, v28, v30, vcc
	v_rsq_f32_e32 v28, v28
	s_nop 0
	v_mul_f32_e32 v30, 0x45800000, v28
	v_cndmask_b32_e32 v42, v28, v30, vcc
	v_pk_mul_f32 v[16:17], v[42:43], v[16:17] op_sel_hi:[0,1]
	v_pk_mul_f32 v[18:19], v[42:43], v[18:19] op_sel_hi:[0,1]
	v_pk_fma_f32 v[18:19], v[88:89], v[18:19], v[46:47]
	v_pk_fma_f32 v[16:17], v[86:87], v[16:17], v[44:45]
	s_and_b64 vcc, exec, s[6:7]
	v_lshl_add_u64 v[44:45], v[94:95], 2, s[0:1]
	s_cbranch_vccnz .LBB0_855
	global_store_dwordx4 v[44:45], v[16:19], off
	s_cbranch_execnz .LBB0_654

.LBB0_665:
	s_waitcnt vmcnt(56)
	v_and_b32_e32 v17, 0xffff0000, v84
	v_and_b32_e32 v19, 0xffff0000, v85
	v_lshlrev_b32_e32 v16, 16, v84
	v_lshlrev_b32_e32 v18, 16, v85
	v_mul_f32_e32 v20, v19, v19
	v_and_b32_e32 v23, 0xffff0000, v83
	v_and_b32_e32 v22, 0xffff0000, v82
	v_and_b32_e32 v29, 0xffff0000, v78
	v_mul_f32_e32 v28, v17, v17
	v_pk_fma_f32 v[42:43], v[18:19], v[18:19], v[20:21] op_sel_hi:[1,1,0]
	v_lshlrev_b32_e32 v21, 16, v83
	v_lshlrev_b32_e32 v20, 16, v82
	v_pk_mul_f32 v[24:25], v[22:23], v[22:23]
	v_lshlrev_b32_e32 v31, 16, v78
	v_pk_fma_f32 v[46:47], v[16:17], v[16:17], v[28:29] op_sel_hi:[1,1,0]
	v_pk_fma_f32 v[44:45], v[20:21], v[20:21], v[24:25]
	v_mov_b32_e32 v30, v46
	v_mov_b32_e32 v48, v42
	v_mov_b32_e32 v49, v31
	v_and_b32_e32 v25, 0xffff0000, v80
	v_mul_f32_e32 v78, v29, v29
	v_pk_add_f32 v[42:43], v[46:47], v[42:43]
	v_pk_mul_f32 v[46:47], v[30:31], v[48:49]
	v_pk_add_f32 v[44:45], v[44:45], v[44:45] op_sel:[0,1] op_sel_hi:[1,0]
	v_lshlrev_b32_e32 v24, 16, v80
	v_and_b32_e32 v27, 0xffff0000, v81
	v_mov_b32_e32 v43, v47
	v_mov_b32_e32 v45, v78
	v_mul_f32_e32 v28, v25, v25
	v_lshlrev_b32_e32 v26, 16, v81
	v_lshlrev_b32_e32 v40, 16, v79
	v_and_b32_e32 v41, 0xffff0000, v79
	v_pk_add_f32 v[42:43], v[42:43], v[44:45]
	v_pk_fma_f32 v[44:45], v[24:25], v[24:25], v[28:29] op_sel_hi:[1,1,0]
	v_mul_f32_e32 v28, v27, v27
	v_mul_f32_e32 v79, v40, v40
	v_mul_f32_e32 v80, v41, v41
	v_pk_fma_f32 v[46:47], v[26:27], v[26:27], v[28:29] op_sel_hi:[1,1,0]
	v_mov_b32_e32 v45, v79
	v_mov_b32_e32 v47, v80
	v_pk_add_f32 v[44:45], v[44:45], v[46:47]
	v_lshlrev_b32_e32 v46, 16, v77
	v_pk_add_f32 v[42:43], v[42:43], v[44:45]
	v_lshlrev_b32_e32 v44, 16, v76
	v_add_f32_e32 v28, v42, v43
	s_nop 1
	v_mov_b32_dpp v30, v28 quad_perm:[1,0,3,2] row_mask:0xf bank_mask:0xf
	v_and_b32_e32 v45, 0xffff0000, v76
	v_and_b32_e32 v47, 0xffff0000, v77
	s_waitcnt lgkmcnt(0)
	v_add_f32_e32 v28, v28, v30
	s_nop 1
	v_mov_b32_dpp v30, v28 quad_perm:[2,3,0,1] row_mask:0xf bank_mask:0xf
	s_waitcnt lgkmcnt(0)
	v_add_f32_e32 v28, v28, v30
	s_nop 1
	v_mov_b32_dpp v30, v28 row_half_mirror row_mask:0xf bank_mask:0xf
	s_waitcnt lgkmcnt(0)
	v_add_f32_e32 v28, v28, v30
	s_nop 1
	v_mov_b32_dpp v30, v28 row_mirror row_mask:0xf bank_mask:0xf
	s_waitcnt lgkmcnt(0)
	v_add_f32_e32 v28, v28, v30
	s_waitcnt lgkmcnt(0)
	s_nop 0
	v_readlane_b32 s98, v28, 32
	v_readlane_b32 s100, v28, 48
	s_nop 1
	v_mov_b32_e32 v30, s100
	v_add_f32_e32 v30, s98, v30
	v_readlane_b32 s98, v28, 0
	v_readlane_b32 s100, v28, 16
	s_nop 1
	v_mov_b32_e32 v28, s100
	v_add_f32_e32 v28, s98, v28
	v_add_f32_e32 v28, v28, v30
	s_waitcnt lgkmcnt(0)
	v_fmamk_f32 v28, v28, 0x3a800000, v247
	v_mul_f32_e32 v30, 0x4b800000, v28
	v_cmp_gt_f32_e32 vcc, s35, v28
	s_nop 1
	v_cndmask_b32_e32 v28, v28, v30, vcc
	v_rsq_f32_e32 v28, v28
	s_nop 0
	v_mul_f32_e32 v30, 0x45800000, v28
	v_cndmask_b32_e32 v42, v28, v30, vcc
	v_pk_mul_f32 v[16:17], v[42:43], v[16:17] op_sel_hi:[0,1]
	v_pk_mul_f32 v[18:19], v[42:43], v[18:19] op_sel_hi:[0,1]
	v_pk_fma_f32 v[18:19], v[88:89], v[18:19], v[46:47]
	v_pk_fma_f32 v[16:17], v[86:87], v[16:17], v[44:45]
	s_and_b64 vcc, exec, s[6:7]
	v_lshl_add_u64 v[44:45], v[66:67], 2, s[0:1]
	s_cbranch_vccnz .LBB0_859
	global_store_dwordx4 v[44:45], v[16:19], off
	s_cbranch_execnz .LBB0_668
